# norm row loop: removed the top-of-row vmcnt(0) store drains so the next row's loads issue while the previous row's stores retire (wait moved to first consumer)
# baseline (speedup 1.0000x reference)
; __device__ __forceinline__ void norm_phase(const Ctx& cx, const Params& p, NormArgs a) {
;     ...
;   for (int q = q0 + wid; q < q1; q += 4) {
;     const int row = row_of(q);
;     int b = row / TPB, t = row % TPB;
;     int v = t < 256 ? 4 : b;
;     const float* PS = PL + 4096 + (v == v0 ? 0 : 6144);
;     float4 h[8];
;     if (a.first) {
;       const float* src = t < 256 ? p.ctx + ((size_t)b * 256 + t) * DM : p.x + ((size_t)b * 2048 + (t - 256)) * DM;
; #pragma unroll
;       for (int i = 0; i < 8; ++i) h[i] = *reinterpret_cast<const float4*>(src + i * 256 + lane * 4);
;     } else {
; #pragma unroll
;       for (int i = 0; i < 8; ++i) {
;         uint2 hb = *reinterpret_cast<const uint2*>(H + (size_t)row * DM + i * 256 + lane * 4);
;         h[i].x = __uint_as_float(hb.x << 16); h[i].y = __uint_as_float(hb.x & 0xffff0000u);
;         h[i].z = __uint_as_float(hb.y << 16); h[i].w = __uint_as_float(hb.y & 0xffff0000u);
;       }
;     }
.LBB0_881:
	s_and_b64 vcc, exec, s[38:39]
	v_mov_b32_e32 v46, v43
	s_cbranch_vccnz .LBB0_883
	v_ashrrev_i32_e32 v0, 11, v43
	v_mul_i32_i24_e32 v0, 0x900, v0
	v_and_b32_e32 v1, 0x7ff, v43
	v_add3_u32 v46, v1, v0, s20
.LBB0_883:
	v_mul_hi_i32 v0, v46, s48
	v_lshrrev_b32_e32 v1, 31, v0
	v_ashrrev_i32_e32 v0, 9, v0
	v_add_u32_e32 v48, v0, v1
	v_mul_i32_i24_e32 v0, 0x900, v48
	v_sub_u32_e32 v51, v46, v0
	v_cmp_gt_i32_e64 s[0:1], s20, v51
	s_mov_b64 s[2:3], -1
	s_and_b64 vcc, exec, s[6:7]
	v_ashrrev_i32_e32 v49, 31, v48
	v_add_u32_e32 v50, 0xffffff00, v51
	s_cbranch_vccz .LBB0_885
	v_mov_b32_e32 v0, s57
	v_mov_b32_e32 v1, s61
	v_ashrrev_i32_e32 v2, 31, v51
	v_cndmask_b32_e64 v1, v0, v1, s[0:1]
	v_mov_b32_e32 v0, s56
	v_mov_b32_e32 v3, s60
	v_cndmask_b32_e64 v4, 24, 21, s[0:1]
	v_cndmask_b32_e64 v0, v0, v3, s[0:1]
	v_cndmask_b32_e64 v3, 0, v2, s[0:1]
	v_cndmask_b32_e64 v2, v50, v51, s[0:1]
	v_lshlrev_b64 v[4:5], v4, v[48:49]
	v_lshl_add_u64 v[0:1], v[0:1], 0, v[4:5]
	v_lshlrev_b64 v[2:3], 13, v[2:3]
	v_lshl_add_u64 v[0:1], v[0:1], 0, v[2:3]
	v_lshlrev_b32_e32 v2, 2, v16
	v_mov_b32_e32 v3, v18
	v_lshl_add_u64 v[0:1], v[0:1], 0, v[2:3]
	s_movk_i32 s2, 0x1000
	global_load_dwordx4 v[32:35], v[0:1], off
	global_load_dwordx4 v[28:31], v[0:1], off offset:1024
	global_load_dwordx4 v[24:27], v[0:1], off offset:2048
	global_load_dwordx4 v[20:23], v[0:1], off offset:3072
	v_add_co_u32_e32 v0, vcc, s2, v0
	s_mov_b64 s[2:3], 0
	s_nop 0
	v_addc_co_u32_e32 v1, vcc, 0, v1, vcc
	global_load_dwordx4 v[12:15], v[0:1], off
	global_load_dwordx4 v[8:11], v[0:1], off offset:1024
	global_load_dwordx4 v[4:7], v[0:1], off offset:2048
	s_nop 0
	global_load_dwordx4 v[0:3], v[0:1], off offset:3072
.LBB0_885:
	s_andn2_b64 vcc, exec, s[2:3]
	v_ashrrev_i32_e32 v47, 31, v46
	s_cbranch_vccnz .LBB0_887
	v_lshlrev_b64 v[0:1], 12, v[46:47]
	v_lshl_add_u64 v[0:1], v[36:37], 0, v[0:1]
	global_load_dwordx2 v[2:3], v[0:1], off
	global_load_dwordx2 v[4:5], v[0:1], off offset:512
	global_load_dwordx2 v[6:7], v[0:1], off offset:1024
	global_load_dwordx2 v[8:9], v[0:1], off offset:1536
	global_load_dwordx2 v[10:11], v[0:1], off offset:2048
	global_load_dwordx2 v[52:53], v[0:1], off offset:2560
	global_load_dwordx2 v[54:55], v[0:1], off offset:3072
	global_load_dwordx2 v[56:57], v[0:1], off offset:3584
	s_and_b64 vcc, exec, s[40:41]
	s_cbranch_vccnz .Lnorm_pf_done
	v_lshlrev_b64 v[164:165], 12, v[46:47]
	v_lshl_add_u64 v[166:167], v[38:39], 0, v[164:165]
	v_lshl_add_u64 v[168:169], v[40:41], 0, v[164:165]
	global_load_dwordx2 v[120:121], v[166:167], off
	global_load_dwordx2 v[122:123], v[166:167], off offset:512
	global_load_dwordx2 v[124:125], v[166:167], off offset:1024
	global_load_dwordx2 v[126:127], v[166:167], off offset:1536
	global_load_dwordx2 v[128:129], v[166:167], off offset:2048
	global_load_dwordx2 v[130:131], v[166:167], off offset:2560
	global_load_dwordx2 v[132:133], v[166:167], off offset:3072
	global_load_dwordx2 v[134:135], v[166:167], off offset:3584
	s_andn2_b64 vcc, exec, s[16:17]
	s_cbranch_vccnz .Lnorm_pf_done
	global_load_dwordx2 v[136:137], v[168:169], off
	global_load_dwordx2 v[138:139], v[168:169], off offset:512
	global_load_dwordx2 v[140:141], v[168:169], off offset:1024
	global_load_dwordx2 v[142:143], v[168:169], off offset:1536
	global_load_dwordx2 v[144:145], v[168:169], off offset:2048
	global_load_dwordx2 v[146:147], v[168:169], off offset:2560
	global_load_dwordx2 v[148:149], v[168:169], off offset:3072
	global_load_dwordx2 v[150:151], v[168:169], off offset:3584
